# differential-attention tile loop as a two-barrier ping-pong (waves 4-7 one barrier behind), 12 MFMAs per half; K staged in the first half, V in the second
# baseline (speedup 1.0000x reference)
.LBB0_927:
	s_lshr_b32 s2, s36, 2
	s_and_b32 s7, s24, 3
	s_and_b32 s2, s2, 1
	s_lshl_b32 s6, s9, 7
	s_lshl_b32 s9, s7, 22
	s_lshl_b32 s16, s2, 13
	s_or_b32 s9, s9, s16
	v_pk_add_f32 v[64:65], v[64:65], 0 op_sel_hi:[1,0]
	v_pk_add_f32 v[66:67], v[66:67], 0 op_sel_hi:[1,0]
	s_add_u32 s16, s30, s9
	v_pk_add_f32 v[64:65], v[68:69], v[64:65]
	v_pk_add_f32 v[66:67], v[70:71], v[66:67]
	s_addc_u32 s17, s31, 0
	s_mul_i32 s2, s2, 0x2080000
	s_lshl_b32 s7, s7, 8
	v_pk_add_f32 v[64:65], v[72:73], v[64:65]
	v_pk_add_f32 v[66:67], v[74:75], v[66:67]
	s_or_b32 s2, s2, s7
	v_pk_add_f32 v[64:65], v[76:77], v[64:65]
	v_pk_add_f32 v[66:67], v[78:79], v[66:67]
	s_add_u32 s18, s34, s2
	v_pk_add_f32 v[64:65], v[80:81], v[64:65]
	v_pk_add_f32 v[66:67], v[82:83], v[66:67]
	s_addc_u32 s19, s35, 0
	s_lshl_b32 s2, s8, 21
	v_pk_add_f32 v[64:65], v[84:85], v[64:65]
	v_pk_add_f32 v[66:67], v[86:87], v[66:67]
	s_add_i32 s7, s2, s29
	v_pk_add_f32 v[64:65], v[88:89], v[64:65]
	v_pk_add_f32 v[66:67], v[90:91], v[66:67]
	s_add_u32 s8, s25, s7
	v_pk_add_f32 v[64:65], v[92:93], v[64:65]
	v_pk_add_f32 v[66:67], v[94:95], v[66:67]
	s_addc_u32 s9, s26, 0
	s_lshl_b32 s2, s6, 1
	v_pk_add_f32 v[64:65], v[64:65], v[66:67]
	s_add_u32 s33, s8, s2
	v_pk_add_f32 v[64:65], v[64:65], v[64:65] op_sel:[0,1] op_sel_hi:[1,0]
	s_addc_u32 s42, s9, 0
	v_mov_b32_e32 v65, v112
	s_add_u32 s7, s27, s7
	v_pk_add_f32 v[166:167], v[64:65], 0 op_sel_hi:[1,0]
	s_addc_u32 s8, s28, 0
	s_lshl_b32 s6, s6, 10
	s_waitcnt lgkmcnt(0)
	s_barrier
	v_xor_b32_e32 v80, 0x80000000, v167
	s_add_u32 s43, s7, s6
	s_mov_b32 s3, 1
	s_addc_u32 s44, s8, 0
	s_mov_b32 s45, 2
	s_mov_b32 s47, 0
	s_mov_b32 s46, 1
	v_mov_b32_e32 v81, v80
	v_mov_b32_e32 v82, v80
	v_mov_b32_e32 v83, v80
	v_mov_b32_e32 v84, v80
	v_mov_b32_e32 v85, v80
	v_mov_b32_e32 v86, v80
	v_mov_b32_e32 v87, v80
	v_mov_b32_e32 v88, v80
	v_mov_b32_e32 v89, v80
	v_mov_b32_e32 v90, v80
	v_mov_b32_e32 v91, v80
	v_mov_b32_e32 v92, v80
	v_mov_b32_e32 v93, v80
	v_mov_b32_e32 v94, v80
	v_mov_b32_e32 v95, v80
	s_waitcnt vmcnt(0)
	v_readfirstlane_b32 s6, v206
	s_cmpk_gt_i32 s6, 0xff
	s_cbranch_scc0 .Ldl_pp_a
	s_barrier
.Ldl_pp_a:
.LBB0_928:
	s_and_b32 s48, s46, 1
	s_mul_i32 s6, s47, 0x4800
	v_add_u32_e32 v69, s6, v175
	s_mul_i32 s6, s48, 0x4400
	v_add_u32_e32 v68, s6, v171
	ds_read_b128 v[72:75], v68
	ds_read_b128 v[76:79], v68 offset:8704
	ds_read_b128 v[222:225], v68 offset:32
	ds_read_b128 v[226:229], v68 offset:8736
	s_xor_b32 s6, s48, 1
	s_mulk_i32 s6, 0x4400
	s_mul_i32 s7, s45, 0x4800
	v_add_u32_e32 v64, s7, v199
	v_add3_u32 v65, s6, v202, v203
	v_add3_u32 v70, s6, v220, v221
	v_add_u32_e32 v230, v64, v201
	v_add_u32_e32 v231, v64, v219
	v_add_u32_e32 v230, 0x8800, v230
	v_add_u32_e32 v231, 0x8800, v231
	s_cmp_lt_u32 s46, 62
	s_cbranch_scc1 .LBB0_930
	s_sub_i32 s40, s46, 62
	s_lshl_b64 s[6:7], s[40:41], 16
	s_add_u32 s6, s33, s6
	s_addc_u32 s7, s42, s7
	s_lshl_b64 s[8:9], s[40:41], 7
	s_add_u32 s22, s43, s8
	s_addc_u32 s23, s44, s9
	s_mov_b64 s[20:21], 0x200
	s_mov_b64 s[8:9], 0x200
	s_branch .LBB0_931

.LBB0_931:
	s_waitcnt lgkmcnt(3)
	v_mfma_f32_32x32x16_bf16 v[112:127], v[72:75], v[140:143], v[80:95]
	ds_read_b128 v[72:75], v68 offset:64
	s_waitcnt vmcnt(2)
	ds_write_b128 v65, v[156:159]
	s_waitcnt lgkmcnt(4)
	v_mfma_f32_32x32x16_bf16 v[240:255], v[76:79], v[140:143], v[80:95]
	ds_read_b128 v[76:79], v68 offset:8768
	ds_write_b128 v70, v[152:155]
	s_waitcnt lgkmcnt(5)
	v_mfma_f32_32x32x16_bf16 v[112:127], v[222:225], v[136:139], v[112:127]
	ds_read_b128 v[222:225], v68 offset:96
	v_lshl_add_u64 v[64:65], s[22:23], 0, v[192:193]
	v_mad_i64_i32 v[66:67], s[22:23], s20, v197, 0
	s_waitcnt lgkmcnt(5)
	v_mfma_f32_32x32x16_bf16 v[240:255], v[226:229], v[136:139], v[240:255]
	ds_read_b128 v[226:229], v68 offset:8800
	v_lshl_add_u64 v[66:67], v[66:67], 1, s[6:7]
	v_lshl_add_u64 v[66:67], v[168:169], 1, v[66:67]
	global_load_dwordx4 v[156:159], v[66:67], off
	s_waitcnt lgkmcnt(5)
	v_mfma_f32_32x32x16_bf16 v[112:127], v[72:75], v[132:135], v[112:127]
	ds_read_b128 v[72:75], v69 offset:34816
	v_mad_i64_i32 v[66:67], s[20:21], s20, v198, 0
	v_lshl_add_u64 v[66:67], v[66:67], 1, s[6:7]
	s_waitcnt lgkmcnt(4)
	v_mfma_f32_32x32x16_bf16 v[240:255], v[76:79], v[132:135], v[240:255]
	ds_read_b128 v[76:79], v69 offset:34848
	v_lshl_add_u64 v[66:67], v[172:173], 1, v[66:67]
	global_load_dwordx4 v[152:155], v[66:67], off
	s_waitcnt lgkmcnt(3)
	v_mfma_f32_32x32x16_bf16 v[112:127], v[222:225], v[128:131], v[112:127]
	ds_read_b128 v[222:225], v69 offset:34880
	v_mad_i64_i32 v[232:233], s[22:23], s8, v170, 0
	v_lshl_add_u64 v[232:233], v[232:233], 1, v[64:65]
	s_waitcnt lgkmcnt(3)
	v_mfma_f32_32x32x16_bf16 v[240:255], v[226:229], v[128:131], v[240:255]
	ds_read_b128 v[226:229], v69 offset:34912
	v_mad_i64_i32 v[234:235], s[6:7], s8, v174, 0
	v_lshl_add_u64 v[234:235], v[234:235], 1, v[64:65]
	s_waitcnt lgkmcnt(3)
	v_mfma_f32_32x32x16_bf16 v[48:63], v[72:75], v[104:107], v[48:63]
	ds_read_b128 v[72:75], v69 offset:39424
	s_mov_b64 s[8:9], 0
	s_waitcnt lgkmcnt(3)
	v_mfma_f32_32x32x16_bf16 v[48:63], v[76:79], v[108:111], v[48:63]
	ds_read_b128 v[76:79], v69 offset:39456
	s_mov_b32 s6, 0x40c00000
	s_waitcnt lgkmcnt(3)
	v_mfma_f32_32x32x16_bf16 v[48:63], v[222:225], v[96:99], v[48:63]
	ds_read_b128 v[222:225], v69 offset:39488
	v_max_f32_e32 v70, v113, v113
	v_max_f32_e32 v71, v112, v112
	v_max_f32_e32 v70, v71, v70
	v_max3_f32 v64, v114, v115, v241
	v_max3_f32 v65, v70, v240, v242
	s_waitcnt lgkmcnt(3)
	v_mfma_f32_32x32x16_bf16 v[48:63], v[226:229], v[100:103], v[48:63]
	ds_read_b128 v[226:229], v69 offset:39520
	v_max3_f32 v65, v65, v243, v116
	v_max3_f32 v64, v64, v118, v119
	v_max3_f32 v65, v65, v117, v244
	v_max3_f32 v64, v64, v246, v247
	v_max3_f32 v65, v65, v245, v120
	s_waitcnt lgkmcnt(10)
	s_barrier
	s_waitcnt lgkmcnt(3)
	v_mfma_f32_32x32x16_bf16 v[32:47], v[72:75], v[104:107], v[32:47]
	ds_read_b128 v[72:75], v69 offset:44032
	s_waitcnt vmcnt(2)
	ds_write2_b64 v230, v[148:149], v[150:151] offset1:2
	v_max3_f32 v64, v64, v122, v123
	v_max3_f32 v65, v65, v121, v248
	s_waitcnt lgkmcnt(4)
	v_mfma_f32_32x32x16_bf16 v[32:47], v[76:79], v[108:111], v[32:47]
	ds_read_b128 v[76:79], v69 offset:44064
	ds_write2_b64 v231, v[144:145], v[146:147] offset1:2
	v_max3_f32 v64, v64, v250, v251
	v_max3_f32 v65, v65, v249, v124
	v_max3_f32 v64, v64, v126, v127
	s_waitcnt lgkmcnt(5)
	v_mfma_f32_32x32x16_bf16 v[32:47], v[222:225], v[96:99], v[32:47]
	ds_read_b128 v[222:225], v69 offset:44096
	global_load_dwordx4 v[148:151], v[232:233], off
	global_load_dwordx4 v[144:147], v[234:235], off
	v_max3_f32 v65, v65, v125, v252
	v_max3_f32 v64, v64, v254, v255
	v_max3_f32 v64, v65, v253, v64
	v_mov_b32_e32 v65, v64
	s_waitcnt lgkmcnt(5)
	v_mfma_f32_32x32x16_bf16 v[32:47], v[226:229], v[100:103], v[32:47]
	ds_read_b128 v[226:229], v69 offset:44128
	v_permlane32_swap_b32_e32 v64, v65
	v_max_f32_e32 v65, v65, v65
	v_max_f32_e32 v64, v64, v64
	v_max_f32_e32 v64, v64, v65
	v_cmp_lt_f32_e32 vcc, s6, v64
	s_cbranch_vccnz .Ldl_rare
	s_waitcnt lgkmcnt(5)
	v_mfma_f32_32x32x16_bf16 v[16:31], v[72:75], v[104:107], v[16:31]
	ds_read_b128 v[72:75], v69 offset:48640
	v_exp_f32_e32 v112, v112
	v_exp_f32_e32 v113, v113
	v_exp_f32_e32 v176, v240
	s_waitcnt lgkmcnt(4)
	v_mfma_f32_32x32x16_bf16 v[16:31], v[76:79], v[108:111], v[16:31]
	ds_read_b128 v[76:79], v69 offset:48672
	v_exp_f32_e32 v177, v241
	v_exp_f32_e32 v114, v114
	v_exp_f32_e32 v115, v115
	s_waitcnt lgkmcnt(3)
	v_mfma_f32_32x32x16_bf16 v[16:31], v[222:225], v[96:99], v[16:31]
	ds_read_b128 v[222:225], v69 offset:48704
	v_exp_f32_e32 v178, v242
	v_exp_f32_e32 v179, v243
	v_exp_f32_e32 v116, v116
	s_waitcnt lgkmcnt(3)
	v_mfma_f32_32x32x16_bf16 v[16:31], v[226:229], v[100:103], v[16:31]
	ds_read_b128 v[226:229], v69 offset:48736
	v_exp_f32_e32 v117, v117
	v_exp_f32_e32 v180, v244
	v_exp_f32_e32 v181, v245
	s_waitcnt lgkmcnt(3)
	v_mfma_f32_32x32x16_bf16 v[0:15], v[72:75], v[104:107], v[0:15]
	v_exp_f32_e32 v118, v118
	v_exp_f32_e32 v119, v119
	v_exp_f32_e32 v182, v246
	s_waitcnt lgkmcnt(2)
	v_mfma_f32_32x32x16_bf16 v[0:15], v[76:79], v[108:111], v[0:15]
	v_exp_f32_e32 v183, v247
	v_exp_f32_e32 v120, v120
	v_exp_f32_e32 v121, v121
	s_waitcnt lgkmcnt(1)
	v_mfma_f32_32x32x16_bf16 v[0:15], v[222:225], v[96:99], v[0:15]
	v_exp_f32_e32 v184, v248
	v_exp_f32_e32 v185, v249
	v_exp_f32_e32 v122, v122
	s_waitcnt lgkmcnt(0)
	v_mfma_f32_32x32x16_bf16 v[0:15], v[226:229], v[100:103], v[0:15]
	v_exp_f32_e32 v123, v123
	v_exp_f32_e32 v186, v250
	v_exp_f32_e32 v187, v251
	v_exp_f32_e32 v124, v124
	v_exp_f32_e32 v125, v125
	v_exp_f32_e32 v188, v252
	v_exp_f32_e32 v189, v253
	v_exp_f32_e32 v126, v126
	v_exp_f32_e32 v127, v127
	v_exp_f32_e32 v190, v254
	v_exp_f32_e32 v191, v255

.Ldl_rare:
	s_waitcnt lgkmcnt(5)
	v_mfma_f32_32x32x16_bf16 v[16:31], v[72:75], v[104:107], v[16:31]
	ds_read_b128 v[72:75], v69 offset:48640
	s_waitcnt lgkmcnt(4)
	v_mfma_f32_32x32x16_bf16 v[16:31], v[76:79], v[108:111], v[16:31]
	ds_read_b128 v[76:79], v69 offset:48672
	s_waitcnt lgkmcnt(3)
	v_mfma_f32_32x32x16_bf16 v[16:31], v[222:225], v[96:99], v[16:31]
	ds_read_b128 v[222:225], v69 offset:48704
	s_waitcnt lgkmcnt(3)
	v_mfma_f32_32x32x16_bf16 v[16:31], v[226:229], v[100:103], v[16:31]
	ds_read_b128 v[226:229], v69 offset:48736
	s_waitcnt lgkmcnt(3)
	v_mfma_f32_32x32x16_bf16 v[0:15], v[72:75], v[104:107], v[0:15]
	s_waitcnt lgkmcnt(2)
	v_mfma_f32_32x32x16_bf16 v[0:15], v[76:79], v[108:111], v[0:15]
	s_waitcnt lgkmcnt(1)
	v_mfma_f32_32x32x16_bf16 v[0:15], v[222:225], v[96:99], v[0:15]
	s_waitcnt lgkmcnt(0)
	v_mfma_f32_32x32x16_bf16 v[0:15], v[226:229], v[100:103], v[0:15]
	v_max_f32_e32 v64, v64, v64
	v_max_f32_e32 v64, 0, v64
	v_exp_f32_e64 v66, -v64
	v_mov_b32_e32 v67, v64
	v_pk_add_f32 v[112:113], v[112:113], v[64:65] op_sel_hi:[1,0] neg_lo:[0,1] neg_hi:[0,1]
	v_pk_add_f32 v[240:241], v[240:241], v[64:65] op_sel_hi:[1,0] neg_lo:[0,1] neg_hi:[0,1]
	v_pk_add_f32 v[114:115], v[114:115], v[64:65] op_sel_hi:[1,0] neg_lo:[0,1] neg_hi:[0,1]
	v_pk_add_f32 v[242:243], v[242:243], v[64:65] op_sel_hi:[1,0] neg_lo:[0,1] neg_hi:[0,1]
	v_pk_add_f32 v[116:117], v[116:117], v[64:65] op_sel_hi:[1,0] neg_lo:[0,1] neg_hi:[0,1]
	v_pk_add_f32 v[244:245], v[244:245], v[64:65] op_sel_hi:[1,0] neg_lo:[0,1] neg_hi:[0,1]
	v_pk_add_f32 v[118:119], v[118:119], v[64:65] op_sel_hi:[1,0] neg_lo:[0,1] neg_hi:[0,1]
	v_pk_add_f32 v[246:247], v[246:247], v[64:65] op_sel_hi:[1,0] neg_lo:[0,1] neg_hi:[0,1]
	v_pk_add_f32 v[120:121], v[120:121], v[64:65] op_sel_hi:[1,0] neg_lo:[0,1] neg_hi:[0,1]
	v_pk_add_f32 v[248:249], v[248:249], v[64:65] op_sel_hi:[1,0] neg_lo:[0,1] neg_hi:[0,1]
	v_pk_add_f32 v[122:123], v[122:123], v[64:65] op_sel_hi:[1,0] neg_lo:[0,1] neg_hi:[0,1]
	v_pk_add_f32 v[250:251], v[250:251], v[64:65] op_sel_hi:[1,0] neg_lo:[0,1] neg_hi:[0,1]
	v_pk_add_f32 v[124:125], v[124:125], v[64:65] op_sel_hi:[1,0] neg_lo:[0,1] neg_hi:[0,1]
	v_pk_add_f32 v[252:253], v[252:253], v[64:65] op_sel_hi:[1,0] neg_lo:[0,1] neg_hi:[0,1]
	v_pk_add_f32 v[126:127], v[126:127], v[64:65] op_sel_hi:[1,0] neg_lo:[0,1] neg_hi:[0,1]
	v_pk_add_f32 v[254:255], v[254:255], v[64:65] op_sel_hi:[1,0] neg_lo:[0,1] neg_hi:[0,1]
	v_pk_add_f32 v[64:65], v[166:167], v[66:67]
	v_pk_mul_f32 v[166:167], v[166:167], v[66:67]
	v_xor_b32_e32 v64, 0x80000000, v65
	v_mov_b32_e32 v167, v65
	v_pk_mul_f32 v[62:63], v[62:63], v[66:67] op_sel_hi:[1,0]
	v_pk_mul_f32 v[60:61], v[60:61], v[66:67] op_sel_hi:[1,0]
	v_pk_mul_f32 v[58:59], v[58:59], v[66:67] op_sel_hi:[1,0]
	v_pk_mul_f32 v[56:57], v[56:57], v[66:67] op_sel_hi:[1,0]
	v_pk_mul_f32 v[54:55], v[54:55], v[66:67] op_sel_hi:[1,0]
	v_pk_mul_f32 v[52:53], v[52:53], v[66:67] op_sel_hi:[1,0]
	v_pk_mul_f32 v[50:51], v[50:51], v[66:67] op_sel_hi:[1,0]
	v_pk_mul_f32 v[48:49], v[48:49], v[66:67] op_sel_hi:[1,0]
	v_pk_mul_f32 v[46:47], v[46:47], v[66:67] op_sel_hi:[1,0]
	v_pk_mul_f32 v[44:45], v[44:45], v[66:67] op_sel_hi:[1,0]
	v_pk_mul_f32 v[42:43], v[42:43], v[66:67] op_sel_hi:[1,0]
	v_pk_mul_f32 v[40:41], v[40:41], v[66:67] op_sel_hi:[1,0]
	v_pk_mul_f32 v[38:39], v[38:39], v[66:67] op_sel_hi:[1,0]
	v_pk_mul_f32 v[36:37], v[36:37], v[66:67] op_sel_hi:[1,0]
	v_pk_mul_f32 v[34:35], v[34:35], v[66:67] op_sel_hi:[1,0]
	v_pk_mul_f32 v[32:33], v[32:33], v[66:67] op_sel_hi:[1,0]
	v_pk_mul_f32 v[30:31], v[30:31], v[66:67] op_sel_hi:[1,0]
	v_pk_mul_f32 v[28:29], v[28:29], v[66:67] op_sel_hi:[1,0]
	v_pk_mul_f32 v[26:27], v[26:27], v[66:67] op_sel_hi:[1,0]
	v_pk_mul_f32 v[24:25], v[24:25], v[66:67] op_sel_hi:[1,0]
	v_pk_mul_f32 v[22:23], v[22:23], v[66:67] op_sel_hi:[1,0]
	v_pk_mul_f32 v[20:21], v[20:21], v[66:67] op_sel_hi:[1,0]
	v_pk_mul_f32 v[18:19], v[18:19], v[66:67] op_sel_hi:[1,0]
	v_pk_mul_f32 v[16:17], v[16:17], v[66:67] op_sel_hi:[1,0]
	v_pk_mul_f32 v[14:15], v[14:15], v[66:67] op_sel_hi:[1,0]
	v_pk_mul_f32 v[12:13], v[12:13], v[66:67] op_sel_hi:[1,0]
	v_pk_mul_f32 v[10:11], v[10:11], v[66:67] op_sel_hi:[1,0]
	v_pk_mul_f32 v[8:9], v[8:9], v[66:67] op_sel_hi:[1,0]
	v_pk_mul_f32 v[6:7], v[6:7], v[66:67] op_sel_hi:[1,0]
	v_pk_mul_f32 v[4:5], v[4:5], v[66:67] op_sel_hi:[1,0]
	v_pk_mul_f32 v[2:3], v[2:3], v[66:67] op_sel_hi:[1,0]
	v_pk_mul_f32 v[0:1], v[0:1], v[66:67] op_sel_hi:[1,0]
	v_mov_b32_e32 v80, v64
	v_mov_b32_e32 v81, v64
	v_mov_b32_e32 v82, v64
	v_mov_b32_e32 v83, v64
	v_mov_b32_e32 v84, v64
	v_mov_b32_e32 v85, v64
	v_mov_b32_e32 v86, v64
	v_mov_b32_e32 v87, v64
	v_mov_b32_e32 v88, v64
	v_mov_b32_e32 v89, v64
	v_mov_b32_e32 v90, v64
	v_mov_b32_e32 v91, v64
	v_mov_b32_e32 v92, v64
	v_mov_b32_e32 v93, v64
	v_mov_b32_e32 v94, v64
	v_mov_b32_e32 v95, v64
	v_exp_f32_e32 v112, v112
	v_exp_f32_e32 v113, v113
	v_exp_f32_e32 v176, v240
	v_exp_f32_e32 v177, v241
	v_exp_f32_e32 v114, v114
	v_exp_f32_e32 v115, v115
	v_exp_f32_e32 v178, v242
	v_exp_f32_e32 v179, v243
	v_exp_f32_e32 v116, v116
	v_exp_f32_e32 v117, v117
	v_exp_f32_e32 v180, v244
	v_exp_f32_e32 v181, v245
	v_exp_f32_e32 v118, v118
	v_exp_f32_e32 v119, v119
	v_exp_f32_e32 v182, v246
	v_exp_f32_e32 v183, v247
	v_exp_f32_e32 v120, v120
	v_exp_f32_e32 v121, v121
	v_exp_f32_e32 v184, v248
	v_exp_f32_e32 v185, v249
	v_exp_f32_e32 v122, v122
	v_exp_f32_e32 v123, v123
	v_exp_f32_e32 v186, v250
	v_exp_f32_e32 v187, v251
	v_exp_f32_e32 v124, v124
	v_exp_f32_e32 v125, v125
	v_exp_f32_e32 v188, v252
	v_exp_f32_e32 v189, v253
	v_exp_f32_e32 v126, v126
	v_exp_f32_e32 v127, v127
	v_exp_f32_e32 v190, v254
	v_exp_f32_e32 v191, v255
	s_branch .Ldl_join
.LBB0_940:
	v_readfirstlane_b32 s6, v206
	s_cmpk_gt_i32 s6, 0xff
	s_cbranch_scc1 .Ldl_pp_b
	s_barrier
